# mlp2 GEMM layer 0 also split: shared tile cut 96/32 k-steps between the workgroup pair (the second one also converts layer-1 weights); layer 1 stays 64/64
# baseline (speedup 1.0000x reference)
.LBB0_828:
	s_cmp_le_i32 s94, s4
	s_cselect_b64 s[0:1], -1, 0
	s_cmp_lt_i32 s4, s95
	s_cselect_b64 s[4:5], -1, 0
	s_and_b64 s[0:1], s[0:1], s[4:5]
	s_andn2_b64 vcc, exec, s[0:1]
	s_cbranch_vccnz .LBB0_150
	s_mov_b64 s[44:45], s[88:89]
	v_mov_b32_e32 v182, v194
	s_load_dwordx2 s[46:47], s[44:45], 0x90
	v_readfirstlane_b32 s42, v182
	s_waitcnt lgkmcnt(0)
	s_add_u32 s30, s46, 0x9000000
	s_addc_u32 s48, s47, 0
	s_and_b64 vcc, exec, s[40:41]
	s_ashr_i32 s40, s42, 6
	s_cbranch_vccnz .LBB0_841
	v_lshlrev_b32_e32 v0, 4, v182
	v_add_u32_e32 v1, 0x2000, v0
	v_ashrrev_i32_e32 v2, 31, v1
	v_lshrrev_b32_e32 v2, 22, v2
	v_add_u32_e32 v2, v1, v2
	s_waitcnt vmcnt(0)
	v_ashrrev_i32_e32 v8, 10, v2
	v_mul_i32_i24_e32 v2, 0x400, v8
	v_sub_u32_e32 v1, v1, v2
	v_lshrrev_b32_e32 v2, 4, v1
	v_bitop3_b32 v1, v2, v1, 32 bitop3:0x6c
	v_ashrrev_i32_e32 v2, 31, v1
	v_lshrrev_b32_e32 v2, 26, v2
	s_add_u32 s41, s46, 0x16000000
	s_mov_b32 s81, s31
	v_add_u32_e32 v2, v1, v2
	v_lshlrev_b32_e32 v3, 3, v8
	s_addc_u32 s43, s47, 0
	s_lshl_b64 s[0:1], s[80:81], 25
	v_ashrrev_i32_e32 v9, 6, v2
	v_and_b32_e32 v3, -16, v3
	s_add_u32 s49, s30, s0
	v_add_u32_e32 v3, v9, v3
	s_addc_u32 s50, s48, s1
	v_and_b32_e32 v4, 3, v9
	s_mov_b32 s1, 0x3ffe0
	v_lshrrev_b32_e32 v5, 2, v3
	v_lshlrev_b32_e32 v6, 1, v3
	v_and_b32_e32 v2, 0xc0, v2
	v_and_or_b32 v4, v3, s1, v4
	v_and_b32_e32 v5, 4, v5
	v_and_b32_e32 v6, 24, v6
	v_sub_u32_e32 v1, v1, v2
	v_or3_b32 v4, v4, v5, v6
	v_lshlrev_b32_e32 v5, 5, v8
	v_ashrrev_i16_sdwa v1, v196, sext(v1) dst_sel:DWORD dst_unused:UNUSED_PAD src0_sel:DWORD src1_sel:BYTE_0
	v_and_b32_e32 v5, 32, v5
	v_bfe_i32 v10, v1, 0, 16
	v_add_lshl_u32 v1, v5, v10, 1
	v_lshl_add_u32 v144, v4, 14, v1
	v_lshl_add_u32 v146, v3, 14, v1
	v_bfe_i32 v1, v182, 27, 1
	v_lshrrev_b32_e32 v1, 22, v1
	v_add_u32_e32 v1, v0, v1
	v_and_b32_e32 v1, 0xfffffc00, v1
	v_sub_u32_e32 v0, v0, v1
	v_lshrrev_b32_e32 v1, 4, v0
	v_ashrrev_i32_e32 v2, 31, v182
	v_bitop3_b32 v0, v1, v0, 32 bitop3:0x6c
	v_lshrrev_b32_e32 v2, 26, v2
	v_ashrrev_i32_e32 v1, 31, v0
	v_add_u32_e32 v2, v182, v2
	v_lshrrev_b32_e32 v1, 26, v1
	v_ashrrev_i32_e32 v12, 6, v2
	v_add_u32_e32 v1, v0, v1
	v_lshlrev_b32_e32 v2, 3, v12
	v_ashrrev_i32_e32 v11, 6, v1
	v_and_b32_e32 v2, -16, v2
	v_add_u32_e32 v2, v11, v2
	v_and_b32_e32 v3, 3, v11
	v_lshrrev_b32_e32 v4, 2, v2
	v_lshlrev_b32_e32 v5, 1, v2
	v_and_b32_e32 v1, 0xc0, v1
	v_and_or_b32 v3, v2, s1, v3
	v_and_b32_e32 v4, 4, v4
	v_and_b32_e32 v5, 24, v5
	v_sub_u32_e32 v0, v0, v1
	s_ashr_i32 s0, s42, 8
	s_lshl_b32 s51, s40, 10
	v_or3_b32 v3, v3, v4, v5
	v_lshlrev_b32_e32 v4, 5, v12
	v_ashrrev_i16_sdwa v0, v196, sext(v0) dst_sel:DWORD dst_unused:UNUSED_PAD src0_sel:DWORD src1_sel:BYTE_0
	s_add_i32 s98, s80, 1
	s_cmp_eq_u32 s66, 0x100
	s_cselect_b32 s98, s98, 0
	v_readlane_b32 s100, v253, 19
	v_readlane_b32 s101, v253, 30
	s_cmp_lt_u32 s2, 0x80
	s_cselect_b32 s4, s98, 0
	s_cmp_eq_u32 s4, 0
	s_cbranch_scc1 .Lm2_first_done
	s_and_b32 s4, s2, 7
	s_mul_i32 s4, s4, 48
	s_lshr_b32 s5, s2, 3
	s_add_i32 s4, s4, s5
	s_add_i32 s4, s4, 32
	s_lshr_b32 s5, s4, 6
	s_and_b32 s4, s4, 63
	s_lshl_b32 s5, s5, 3
	s_and_b32 s101, s4, 7
	s_add_i32 s101, s101, s5
	s_lshr_b32 s100, s4, 3

.LBB0_835:
	s_ashr_i32 s17, s16, 31
	s_lshl_b64 s[6:7], s[16:17], 22
	s_add_u32 s24, s41, s6
	v_cmp_lt_i64_e32 vcc, s[14:15], v[160:161]
	s_addc_u32 s25, s43, s7
	s_ashr_i32 s1, s0, 31
	s_lshl_b64 s[14:15], s[0:1], 22
	s_add_u32 s14, s49, s14
	s_addc_u32 s15, s50, s15
	s_lshl_b32 s101, s98, 12
	s_sub_u32 s101, 0x4000, s101
	s_cmp_ge_u32 s2, 0x80
	s_cselect_b32 s100, s101, 0
	s_cmp_eq_u32 s62, 1
	s_cselect_b32 s100, s100, 0
	s_cmp_lg_u32 s98, 0
	s_cselect_b32 s100, s100, 0
	s_add_u32 s24, s24, s100
	s_addc_u32 s25, s25, 0
	s_add_u32 s14, s14, s100
	s_addc_u32 s15, s15, 0
	s_and_b64 s[6:7], vcc, exec
	s_cselect_b32 s6, s25, s21
	s_cselect_b32 s7, s24, s20
	s_and_b64 s[34:35], vcc, exec
	s_cselect_b32 s1, s15, s23
	s_cselect_b32 s17, s14, s22
	s_cmp_lt_u32 s2, 0x80
	s_cselect_b32 s99, 1, 2
	s_cmp_eq_u32 s62, s99
	s_cselect_b32 s99, s99, 0
	s_cmp_lg_u32 s98, 0
	s_cselect_b32 s99, s99, 0
	s_add_u32 s20, s20, 0x200080
	s_addc_u32 s21, s21, 0
	s_add_u32 s63, s22, 0x100
	v_mov_b32_e32 v0, 0
	s_addc_u32 s68, s23, 0
	s_lshl_b32 s101, s98, 5
	s_sub_i32 s100, 0x7e, s101
	s_add_i32 s101, s101, -2
	s_cmp_eq_u32 s99, 1
	s_cselect_b32 s69, s101, s100
	s_cmp_eq_u32 s99, 0
	s_cselect_b32 s69, -2, s69
	v_mov_b32_e32 v1, v0
	v_mov_b32_e32 v2, v0
	v_mov_b32_e32 v3, v0
	v_mov_b32_e32 v4, v0
	v_mov_b32_e32 v5, v0
	v_mov_b32_e32 v6, v0
	v_mov_b32_e32 v7, v0
	v_mov_b32_e32 v12, v0
	v_mov_b32_e32 v13, v0
	v_mov_b32_e32 v14, v0
	v_mov_b32_e32 v15, v0
	v_mov_b32_e32 v20, v0
	v_mov_b32_e32 v21, v0
	v_mov_b32_e32 v22, v0
	v_mov_b32_e32 v23, v0
	v_mov_b32_e32 v28, v0
	v_mov_b32_e32 v29, v0
	v_mov_b32_e32 v30, v0
	v_mov_b32_e32 v31, v0
	v_mov_b32_e32 v36, v0
	v_mov_b32_e32 v37, v0
	v_mov_b32_e32 v38, v0
	v_mov_b32_e32 v39, v0
	v_mov_b32_e32 v44, v0
	v_mov_b32_e32 v45, v0
	v_mov_b32_e32 v46, v0
	v_mov_b32_e32 v47, v0
	v_mov_b32_e32 v52, v0
	v_mov_b32_e32 v53, v0
	v_mov_b32_e32 v54, v0
	v_mov_b32_e32 v55, v0
	v_mov_b32_e32 v8, v0
	v_mov_b32_e32 v9, v0
	v_mov_b32_e32 v10, v0
	v_mov_b32_e32 v11, v0
	v_mov_b32_e32 v16, v0
	v_mov_b32_e32 v17, v0
	v_mov_b32_e32 v18, v0
	v_mov_b32_e32 v19, v0
	v_mov_b32_e32 v24, v0
	v_mov_b32_e32 v25, v0
	v_mov_b32_e32 v26, v0
	v_mov_b32_e32 v27, v0
	v_mov_b32_e32 v32, v0
	v_mov_b32_e32 v33, v0
	v_mov_b32_e32 v34, v0
	v_mov_b32_e32 v35, v0
	v_mov_b32_e32 v40, v0
	v_mov_b32_e32 v41, v0
	v_mov_b32_e32 v42, v0
	v_mov_b32_e32 v43, v0
	v_mov_b32_e32 v48, v0
	v_mov_b32_e32 v49, v0
	v_mov_b32_e32 v50, v0
	v_mov_b32_e32 v51, v0
	v_mov_b32_e32 v56, v0
	v_mov_b32_e32 v57, v0
	v_mov_b32_e32 v58, v0
	v_mov_b32_e32 v59, v0
	v_mov_b32_e32 v60, v0
	v_mov_b32_e32 v61, v0
	v_mov_b32_e32 v62, v0
	v_mov_b32_e32 v63, v0
	v_mov_b32_e32 v64, v0
	v_mov_b32_e32 v65, v0
	v_mov_b32_e32 v66, v0
	v_mov_b32_e32 v67, v0
	v_mov_b32_e32 v68, v0
	v_mov_b32_e32 v69, v0
	v_mov_b32_e32 v70, v0
	v_mov_b32_e32 v71, v0
	v_mov_b32_e32 v76, v0
	v_mov_b32_e32 v77, v0
	v_mov_b32_e32 v78, v0
	v_mov_b32_e32 v79, v0
	v_mov_b32_e32 v84, v0
	v_mov_b32_e32 v85, v0
	v_mov_b32_e32 v86, v0
	v_mov_b32_e32 v87, v0
	v_mov_b32_e32 v92, v0
	v_mov_b32_e32 v93, v0
	v_mov_b32_e32 v94, v0
	v_mov_b32_e32 v95, v0
	v_mov_b32_e32 v100, v0
	v_mov_b32_e32 v101, v0
	v_mov_b32_e32 v102, v0
	v_mov_b32_e32 v103, v0
	v_mov_b32_e32 v108, v0
	v_mov_b32_e32 v109, v0
	v_mov_b32_e32 v110, v0
	v_mov_b32_e32 v111, v0
	v_mov_b32_e32 v116, v0
	v_mov_b32_e32 v117, v0
	v_mov_b32_e32 v118, v0
	v_mov_b32_e32 v119, v0
	v_mov_b32_e32 v72, v0
	v_mov_b32_e32 v73, v0
	v_mov_b32_e32 v74, v0
	v_mov_b32_e32 v75, v0
	v_mov_b32_e32 v80, v0
	v_mov_b32_e32 v81, v0
	v_mov_b32_e32 v82, v0
	v_mov_b32_e32 v83, v0
	v_mov_b32_e32 v88, v0
	v_mov_b32_e32 v89, v0
	v_mov_b32_e32 v90, v0
	v_mov_b32_e32 v91, v0
	v_mov_b32_e32 v96, v0
	v_mov_b32_e32 v97, v0
	v_mov_b32_e32 v98, v0
	v_mov_b32_e32 v99, v0
	v_mov_b32_e32 v104, v0
	v_mov_b32_e32 v105, v0
	v_mov_b32_e32 v106, v0
	v_mov_b32_e32 v107, v0
	v_mov_b32_e32 v112, v0
	v_mov_b32_e32 v113, v0
	v_mov_b32_e32 v114, v0
	v_mov_b32_e32 v115, v0
	v_mov_b32_e32 v128, v0
	v_mov_b32_e32 v129, v0
	v_mov_b32_e32 v130, v0
	v_mov_b32_e32 v131, v0
	v_mov_b32_e32 v140, v0
	v_mov_b32_e32 v141, v0
	v_mov_b32_e32 v142, v0
	v_mov_b32_e32 v143, v0
.LBB0_836:
	s_add_u32 s22, s20, 0xffe00080
	s_addc_u32 s23, s21, -1
	s_add_i32 s78, 0, 0x10000
	v_add_u32_e32 v136, s78, v183
	ds_read_b128 v[120:123], v136
	ds_read_b128 v[124:127], v136 offset:1024
	ds_read_b128 v[132:135], v136 offset:2048
	ds_read_b128 v[136:139], v136 offset:3072
	s_cmpk_eq_i32 s69, 0x7c
	s_cselect_b32 s35, s6, s23
	s_cselect_b32 s34, s7, s22
	s_cselect_b32 s23, s1, s68
	s_cselect_b32 s22, s17, s63
	v_lshl_add_u64 v[180:181], s[20:21], 0, v[176:177]
	s_add_i32 m0, s52, 0xc000
	ds_read_b128 v[186:189], v185
	ds_read_b128 v[190:193], v185 offset:1024
	ds_read_b128 v[206:209], v185 offset:2048
	ds_read_b128 v[210:213], v185 offset:3072
	ds_read_b128 v[214:217], v185 offset:4096
	ds_read_b128 v[218:221], v185 offset:5120
	ds_read_b128 v[222:225], v185 offset:6144
	ds_read_b128 v[226:229], v185 offset:7168
	global_load_lds_dwordx4 v[180:181], off
	v_lshl_add_u64 v[180:181], s[20:21], 0, v[178:179]
	s_add_i32 m0, s52, 0xe000
	s_nop 0
	global_load_lds_dwordx4 v[180:181], off
	s_waitcnt lgkmcnt(8)
	s_barrier
	s_waitcnt lgkmcnt(0)
	s_setprio 1
	s_waitcnt lgkmcnt(0)
	v_mfma_f32_16x16x32_bf16 v[140:143], v[120:123], v[186:189], v[140:143]
	v_mfma_f32_16x16x32_bf16 v[128:131], v[132:135], v[186:189], v[128:131]
	v_mfma_f32_16x16x32_bf16 v[112:115], v[120:123], v[206:209], v[112:115]
	v_mfma_f32_16x16x32_bf16 v[104:107], v[132:135], v[206:209], v[104:107]
	v_mfma_f32_16x16x32_bf16 v[96:99], v[120:123], v[214:217], v[96:99]
	v_mfma_f32_16x16x32_bf16 v[88:91], v[132:135], v[214:217], v[88:91]
	v_mfma_f32_16x16x32_bf16 v[80:83], v[120:123], v[222:225], v[80:83]
	v_mfma_f32_16x16x32_bf16 v[72:75], v[132:135], v[222:225], v[72:75]
	v_mfma_f32_16x16x32_bf16 v[140:143], v[124:127], v[190:193], v[140:143]
	v_mfma_f32_16x16x32_bf16 v[128:131], v[136:139], v[190:193], v[128:131]
	v_mfma_f32_16x16x32_bf16 v[112:115], v[124:127], v[210:213], v[112:115]
	v_mfma_f32_16x16x32_bf16 v[104:107], v[136:139], v[210:213], v[104:107]
	v_mfma_f32_16x16x32_bf16 v[96:99], v[124:127], v[218:221], v[96:99]
	v_mfma_f32_16x16x32_bf16 v[88:91], v[136:139], v[218:221], v[88:91]
	v_mfma_f32_16x16x32_bf16 v[80:83], v[124:127], v[226:229], v[80:83]
	v_mfma_f32_16x16x32_bf16 v[72:75], v[136:139], v[226:229], v[72:75]
	s_setprio 0
	s_barrier
	s_add_i32 s80, 0, 0x14000
	v_add_u32_e32 v180, s80, v183
	s_add_i32 s78, s78, s51
	ds_read_b128 v[230:233], v180
	ds_read_b128 v[234:237], v180 offset:1024
	ds_read_b128 v[238:241], v180 offset:2048
	ds_read_b128 v[242:245], v180 offset:3072
	v_lshl_add_u64 v[180:181], s[22:23], 0, v[152:153]
	s_mov_b32 m0, s78
	v_lshl_add_u64 v[246:247], s[22:23], 0, v[144:145]
	global_load_lds_dwordx4 v[180:181], off
	s_add_i32 m0, s78, 0x2000
	s_nop 0
	global_load_lds_dwordx4 v[246:247], off
	s_barrier
	s_waitcnt lgkmcnt(0)
	s_setprio 1
	s_waitcnt lgkmcnt(0)
	v_mfma_f32_16x16x32_bf16 v[116:119], v[230:233], v[186:189], v[116:119]
	v_mfma_f32_16x16x32_bf16 v[108:111], v[238:241], v[186:189], v[108:111]
	v_mfma_f32_16x16x32_bf16 v[100:103], v[230:233], v[206:209], v[100:103]
	v_mfma_f32_16x16x32_bf16 v[92:95], v[238:241], v[206:209], v[92:95]
	v_mfma_f32_16x16x32_bf16 v[84:87], v[230:233], v[214:217], v[84:87]
	v_mfma_f32_16x16x32_bf16 v[76:79], v[238:241], v[214:217], v[76:79]
	v_mfma_f32_16x16x32_bf16 v[68:71], v[230:233], v[222:225], v[68:71]
	v_mfma_f32_16x16x32_bf16 v[64:67], v[238:241], v[222:225], v[64:67]
	v_mfma_f32_16x16x32_bf16 v[116:119], v[234:237], v[190:193], v[116:119]
	v_mfma_f32_16x16x32_bf16 v[108:111], v[242:245], v[190:193], v[108:111]
	v_mfma_f32_16x16x32_bf16 v[100:103], v[234:237], v[210:213], v[100:103]
	v_mfma_f32_16x16x32_bf16 v[92:95], v[242:245], v[210:213], v[92:95]
	v_mfma_f32_16x16x32_bf16 v[84:87], v[234:237], v[218:221], v[84:87]
	v_mfma_f32_16x16x32_bf16 v[76:79], v[242:245], v[218:221], v[76:79]
	v_mfma_f32_16x16x32_bf16 v[68:71], v[234:237], v[226:229], v[68:71]
	v_mfma_f32_16x16x32_bf16 v[64:67], v[242:245], v[226:229], v[64:67]
	s_setprio 0
	s_mov_b32 m0, s52
	v_lshl_add_u64 v[248:249], s[34:35], 0, v[148:149]
	s_barrier
	ds_read_b128 v[186:189], v185 offset:16384
	ds_read_b128 v[190:193], v185 offset:17408
	ds_read_b128 v[206:209], v185 offset:18432
	ds_read_b128 v[210:213], v185 offset:19456
	ds_read_b128 v[214:217], v185 offset:20480
	ds_read_b128 v[218:221], v185 offset:21504
	ds_read_b128 v[222:225], v185 offset:22528
	ds_read_b128 v[226:229], v185 offset:23552
	global_load_lds_dwordx4 v[248:249], off
	v_lshl_add_u64 v[250:251], s[34:35], 0, v[146:147]
	s_mov_b32 m0, s53
	s_nop 0
	global_load_lds_dwordx4 v[250:251], off
	s_barrier
	s_waitcnt lgkmcnt(0)
	s_setprio 1
	s_waitcnt lgkmcnt(0)
	v_mfma_f32_16x16x32_bf16 v[60:63], v[120:123], v[186:189], v[60:63]
	v_mfma_f32_16x16x32_bf16 v[56:59], v[132:135], v[186:189], v[56:59]
	v_mfma_f32_16x16x32_bf16 v[48:51], v[120:123], v[206:209], v[48:51]
	v_mfma_f32_16x16x32_bf16 v[40:43], v[132:135], v[206:209], v[40:43]
	v_mfma_f32_16x16x32_bf16 v[32:35], v[120:123], v[214:217], v[32:35]
	v_mfma_f32_16x16x32_bf16 v[24:27], v[132:135], v[214:217], v[24:27]
	v_mfma_f32_16x16x32_bf16 v[16:19], v[120:123], v[222:225], v[16:19]
	v_mfma_f32_16x16x32_bf16 v[8:11], v[132:135], v[222:225], v[8:11]
	v_mfma_f32_16x16x32_bf16 v[60:63], v[124:127], v[190:193], v[60:63]
	v_mfma_f32_16x16x32_bf16 v[56:59], v[136:139], v[190:193], v[56:59]
	v_mfma_f32_16x16x32_bf16 v[48:51], v[124:127], v[210:213], v[48:51]
	v_mfma_f32_16x16x32_bf16 v[40:43], v[136:139], v[210:213], v[40:43]
	v_mfma_f32_16x16x32_bf16 v[32:35], v[124:127], v[218:221], v[32:35]
	v_mfma_f32_16x16x32_bf16 v[24:27], v[136:139], v[218:221], v[24:27]
	v_mfma_f32_16x16x32_bf16 v[16:19], v[124:127], v[226:229], v[16:19]
	v_mfma_f32_16x16x32_bf16 v[8:11], v[136:139], v[226:229], v[8:11]
	s_setprio 0
	s_barrier
	s_add_u32 s78, s22, 0x200000
	s_addc_u32 s79, s23, 0
	s_add_i32 s80, s80, s51
	v_lshl_add_u64 v[120:121], s[78:79], 0, v[152:153]
	s_mov_b32 m0, s80
	s_nop 0
	global_load_lds_dwordx4 v[120:121], off
	v_lshl_add_u64 v[120:121], s[78:79], 0, v[144:145]
	s_add_i32 m0, s80, 0x2000
	s_nop 0
	global_load_lds_dwordx4 v[120:121], off
	s_waitcnt vmcnt(6)
	s_barrier
	s_setprio 1
	v_mfma_f32_16x16x32_bf16 v[52:55], v[230:233], v[186:189], v[52:55]
	v_mfma_f32_16x16x32_bf16 v[44:47], v[238:241], v[186:189], v[44:47]
	v_mfma_f32_16x16x32_bf16 v[36:39], v[230:233], v[206:209], v[36:39]
	v_mfma_f32_16x16x32_bf16 v[28:31], v[238:241], v[206:209], v[28:31]
	v_mfma_f32_16x16x32_bf16 v[20:23], v[230:233], v[214:217], v[20:23]
	v_mfma_f32_16x16x32_bf16 v[12:15], v[238:241], v[214:217], v[12:15]
	v_mfma_f32_16x16x32_bf16 v[4:7], v[230:233], v[222:225], v[4:7]
	v_mfma_f32_16x16x32_bf16 v[0:3], v[238:241], v[222:225], v[0:3]
	v_mfma_f32_16x16x32_bf16 v[52:55], v[234:237], v[190:193], v[52:55]
	v_mfma_f32_16x16x32_bf16 v[44:47], v[242:245], v[190:193], v[44:47]
	v_mfma_f32_16x16x32_bf16 v[36:39], v[234:237], v[210:213], v[36:39]
	v_mfma_f32_16x16x32_bf16 v[28:31], v[242:245], v[210:213], v[28:31]
	v_mfma_f32_16x16x32_bf16 v[20:23], v[234:237], v[218:221], v[20:23]
	v_mfma_f32_16x16x32_bf16 v[12:15], v[242:245], v[218:221], v[12:15]
	v_mfma_f32_16x16x32_bf16 v[4:7], v[234:237], v[226:229], v[4:7]
	v_mfma_f32_16x16x32_bf16 v[0:3], v[242:245], v[226:229], v[0:3]
	s_setprio 0
	s_add_i32 s78, 0, 0x18000
	v_add_u32_e32 v136, s78, v183
	s_barrier
	ds_read_b128 v[120:123], v136
	ds_read_b128 v[124:127], v136 offset:1024
	ds_read_b128 v[132:135], v136 offset:2048
	ds_read_b128 v[136:139], v136 offset:3072
	s_add_u32 s34, s34, 0x200000
	s_addc_u32 s35, s35, 0
	s_mov_b32 m0, s54
	v_lshl_add_u64 v[230:231], s[34:35], 0, v[148:149]
	ds_read_b128 v[186:189], v185 offset:32768
	ds_read_b128 v[190:193], v185 offset:33792
	ds_read_b128 v[206:209], v185 offset:34816
	ds_read_b128 v[210:213], v185 offset:35840
	ds_read_b128 v[214:217], v185 offset:36864
	ds_read_b128 v[218:221], v185 offset:37888
	ds_read_b128 v[222:225], v185 offset:38912
	ds_read_b128 v[226:229], v185 offset:39936
	global_load_lds_dwordx4 v[230:231], off
	v_lshl_add_u64 v[230:231], s[34:35], 0, v[146:147]
	s_mov_b32 m0, s55
	s_nop 0
	global_load_lds_dwordx4 v[230:231], off
	s_waitcnt lgkmcnt(8)
	s_barrier
	s_waitcnt lgkmcnt(0)
	s_setprio 1
	s_waitcnt lgkmcnt(0)
	v_mfma_f32_16x16x32_bf16 v[140:143], v[120:123], v[186:189], v[140:143]
	v_mfma_f32_16x16x32_bf16 v[128:131], v[132:135], v[186:189], v[128:131]
	v_mfma_f32_16x16x32_bf16 v[112:115], v[120:123], v[206:209], v[112:115]
	v_mfma_f32_16x16x32_bf16 v[104:107], v[132:135], v[206:209], v[104:107]
	v_mfma_f32_16x16x32_bf16 v[96:99], v[120:123], v[214:217], v[96:99]
	v_mfma_f32_16x16x32_bf16 v[88:91], v[132:135], v[214:217], v[88:91]
	v_mfma_f32_16x16x32_bf16 v[80:83], v[120:123], v[222:225], v[80:83]
	v_mfma_f32_16x16x32_bf16 v[72:75], v[132:135], v[222:225], v[72:75]
	v_mfma_f32_16x16x32_bf16 v[140:143], v[124:127], v[190:193], v[140:143]
	v_mfma_f32_16x16x32_bf16 v[128:131], v[136:139], v[190:193], v[128:131]
	v_mfma_f32_16x16x32_bf16 v[112:115], v[124:127], v[210:213], v[112:115]
	v_mfma_f32_16x16x32_bf16 v[104:107], v[136:139], v[210:213], v[104:107]
	v_mfma_f32_16x16x32_bf16 v[96:99], v[124:127], v[218:221], v[96:99]
	v_mfma_f32_16x16x32_bf16 v[88:91], v[136:139], v[218:221], v[88:91]
	v_mfma_f32_16x16x32_bf16 v[80:83], v[124:127], v[226:229], v[80:83]
	v_mfma_f32_16x16x32_bf16 v[72:75], v[136:139], v[226:229], v[72:75]
	s_setprio 0
	s_barrier
	s_add_i32 s34, 0, 0x1c000
	s_add_i32 s35, s78, s51
	v_add_u32_e32 v205, s34, v183
	v_lshl_add_u64 v[180:181], v[180:181], 0, s[18:19]
	s_mov_b32 m0, s35
	ds_read_b128 v[230:233], v205
	ds_read_b128 v[234:237], v205 offset:1024
	ds_read_b128 v[238:241], v205 offset:2048
	ds_read_b128 v[242:245], v205 offset:3072
	global_load_lds_dwordx4 v[180:181], off
	v_lshl_add_u64 v[180:181], v[246:247], 0, s[18:19]
	s_add_i32 m0, s35, 0x2000
	s_nop 0
	global_load_lds_dwordx4 v[180:181], off
	s_barrier
	s_waitcnt lgkmcnt(0)
	s_setprio 1
	s_waitcnt lgkmcnt(0)
	v_mfma_f32_16x16x32_bf16 v[116:119], v[230:233], v[186:189], v[116:119]
	v_mfma_f32_16x16x32_bf16 v[108:111], v[238:241], v[186:189], v[108:111]
	v_mfma_f32_16x16x32_bf16 v[100:103], v[230:233], v[206:209], v[100:103]
	v_mfma_f32_16x16x32_bf16 v[92:95], v[238:241], v[206:209], v[92:95]
	v_mfma_f32_16x16x32_bf16 v[84:87], v[230:233], v[214:217], v[84:87]
	v_mfma_f32_16x16x32_bf16 v[76:79], v[238:241], v[214:217], v[76:79]
	v_mfma_f32_16x16x32_bf16 v[68:71], v[230:233], v[222:225], v[68:71]
	v_mfma_f32_16x16x32_bf16 v[64:67], v[238:241], v[222:225], v[64:67]
	v_mfma_f32_16x16x32_bf16 v[116:119], v[234:237], v[190:193], v[116:119]
	v_mfma_f32_16x16x32_bf16 v[108:111], v[242:245], v[190:193], v[108:111]
	v_mfma_f32_16x16x32_bf16 v[100:103], v[234:237], v[210:213], v[100:103]
	v_mfma_f32_16x16x32_bf16 v[92:95], v[242:245], v[210:213], v[92:95]
	v_mfma_f32_16x16x32_bf16 v[84:87], v[234:237], v[218:221], v[84:87]
	v_mfma_f32_16x16x32_bf16 v[76:79], v[242:245], v[218:221], v[76:79]
	v_mfma_f32_16x16x32_bf16 v[68:71], v[234:237], v[226:229], v[68:71]
	v_mfma_f32_16x16x32_bf16 v[64:67], v[242:245], v[226:229], v[64:67]
	s_setprio 0
	s_mov_b32 m0, s60
	v_lshl_add_u64 v[180:181], v[248:249], 0, s[18:19]
	s_barrier
	ds_read_b128 v[186:189], v185 offset:49152
	ds_read_b128 v[190:193], v185 offset:50176
	ds_read_b128 v[206:209], v185 offset:51200
	ds_read_b128 v[210:213], v185 offset:52224
	ds_read_b128 v[214:217], v185 offset:53248
	ds_read_b128 v[218:221], v185 offset:54272
	ds_read_b128 v[222:225], v185 offset:55296
	ds_read_b128 v[226:229], v185 offset:56320
	global_load_lds_dwordx4 v[180:181], off
	v_lshl_add_u64 v[180:181], v[250:251], 0, s[18:19]
	s_mov_b32 m0, s61
	s_nop 0
	global_load_lds_dwordx4 v[180:181], off
	s_barrier
	s_waitcnt lgkmcnt(0)
	s_setprio 1
	s_waitcnt lgkmcnt(0)
	v_mfma_f32_16x16x32_bf16 v[60:63], v[120:123], v[186:189], v[60:63]
	v_mfma_f32_16x16x32_bf16 v[56:59], v[132:135], v[186:189], v[56:59]
	v_mfma_f32_16x16x32_bf16 v[48:51], v[120:123], v[206:209], v[48:51]
	v_mfma_f32_16x16x32_bf16 v[40:43], v[132:135], v[206:209], v[40:43]
	v_mfma_f32_16x16x32_bf16 v[32:35], v[120:123], v[214:217], v[32:35]
	v_mfma_f32_16x16x32_bf16 v[24:27], v[132:135], v[214:217], v[24:27]
	v_mfma_f32_16x16x32_bf16 v[16:19], v[120:123], v[222:225], v[16:19]
	v_mfma_f32_16x16x32_bf16 v[8:11], v[132:135], v[222:225], v[8:11]
	v_mfma_f32_16x16x32_bf16 v[60:63], v[124:127], v[190:193], v[60:63]
	v_mfma_f32_16x16x32_bf16 v[56:59], v[136:139], v[190:193], v[56:59]
	v_mfma_f32_16x16x32_bf16 v[48:51], v[124:127], v[210:213], v[48:51]
	v_mfma_f32_16x16x32_bf16 v[40:43], v[136:139], v[210:213], v[40:43]
	v_mfma_f32_16x16x32_bf16 v[32:35], v[124:127], v[218:221], v[32:35]
	v_mfma_f32_16x16x32_bf16 v[24:27], v[136:139], v[218:221], v[24:27]
	v_mfma_f32_16x16x32_bf16 v[16:19], v[124:127], v[226:229], v[16:19]
	v_mfma_f32_16x16x32_bf16 v[8:11], v[136:139], v[226:229], v[8:11]
	s_setprio 0
	s_barrier
	s_add_u32 s22, s22, 0x200080
	s_addc_u32 s23, s23, 0
	s_add_i32 s34, s34, s51
	v_lshl_add_u64 v[120:121], s[22:23], 0, v[152:153]
	s_mov_b32 m0, s34
	s_nop 0
	global_load_lds_dwordx4 v[120:121], off
	v_lshl_add_u64 v[120:121], s[22:23], 0, v[144:145]
	s_add_i32 m0, s34, 0x2000
	s_nop 0
	global_load_lds_dwordx4 v[120:121], off
	s_waitcnt vmcnt(6)
	s_barrier
	s_setprio 1
	v_mfma_f32_16x16x32_bf16 v[52:55], v[230:233], v[186:189], v[52:55]
	v_mfma_f32_16x16x32_bf16 v[44:47], v[238:241], v[186:189], v[44:47]
	v_mfma_f32_16x16x32_bf16 v[36:39], v[230:233], v[206:209], v[36:39]
	v_mfma_f32_16x16x32_bf16 v[28:31], v[238:241], v[206:209], v[28:31]
	v_mfma_f32_16x16x32_bf16 v[20:23], v[230:233], v[214:217], v[20:23]
	v_mfma_f32_16x16x32_bf16 v[12:15], v[238:241], v[214:217], v[12:15]
	v_mfma_f32_16x16x32_bf16 v[4:7], v[230:233], v[222:225], v[4:7]
	v_mfma_f32_16x16x32_bf16 v[0:3], v[238:241], v[222:225], v[0:3]
	v_mfma_f32_16x16x32_bf16 v[52:55], v[234:237], v[190:193], v[52:55]
	v_mfma_f32_16x16x32_bf16 v[44:47], v[242:245], v[190:193], v[44:47]
	v_mfma_f32_16x16x32_bf16 v[36:39], v[234:237], v[210:213], v[36:39]
	v_mfma_f32_16x16x32_bf16 v[28:31], v[242:245], v[210:213], v[28:31]
	v_mfma_f32_16x16x32_bf16 v[20:23], v[234:237], v[218:221], v[20:23]
	v_mfma_f32_16x16x32_bf16 v[12:15], v[242:245], v[218:221], v[12:15]
	v_mfma_f32_16x16x32_bf16 v[4:7], v[234:237], v[226:229], v[4:7]
	v_mfma_f32_16x16x32_bf16 v[0:3], v[242:245], v[226:229], v[0:3]
	s_setprio 0
	s_add_i32 s69, s69, 2
	s_add_u32 s20, s20, 0x100
	s_addc_u32 s21, s21, 0
	s_add_u32 s63, s63, 0x100
	s_addc_u32 s68, s68, 0
	s_cmpk_gt_u32 s69, 0x7d
	s_barrier
	s_cbranch_scc0 .LBB0_836
	s_cmp_eq_u32 s99, 0
	s_cbranch_scc1 .Lm2_epi
	s_and_b32 s100, s2, 0x7f
	s_lshl_b32 s100, s100, 18
	s_add_u32 s100, s100, 0x29800000
	s_add_u32 s100, s46, s100
	s_addc_u32 s101, s47, 0
	v_lshlrev_b32_e32 v186, 4, v182
	s_cmp_eq_u32 s99, 1
	s_cbranch_scc1 .Lm2_put_partial
	s_and_b32 s6, s2, 0x7f
	s_lshl_b32 s6, s6, 6
	s_lshl_b32 s7, s98, 14
	s_add_u32 s6, s6, s7
	s_add_u32 s6, s6, 0x29702000
	s_add_u32 s6, s46, s6
	s_addc_u32 s7, s47, 0
	v_mov_b32_e32 v187, 0
	s_mov_b32 s99, 0

.Lm2_put_partial:
	s_nop 7
	s_nop 7
	global_store_dwordx4 v186, v[140:143], s[100:101]
	s_add_u32 s100, s100, 0x2000
	s_addc_u32 s101, s101, 0
	global_store_dwordx4 v186, v[128:131], s[100:101]
	s_add_u32 s100, s100, 0x2000
	s_addc_u32 s101, s101, 0
	global_store_dwordx4 v186, v[116:119], s[100:101]
	s_add_u32 s100, s100, 0x2000
	s_addc_u32 s101, s101, 0
	global_store_dwordx4 v186, v[108:111], s[100:101]
	s_add_u32 s100, s100, 0x2000
	s_addc_u32 s101, s101, 0
	global_store_dwordx4 v186, v[112:115], s[100:101]
	s_add_u32 s100, s100, 0x2000
	s_addc_u32 s101, s101, 0
	global_store_dwordx4 v186, v[104:107], s[100:101]
	s_add_u32 s100, s100, 0x2000
	s_addc_u32 s101, s101, 0
	global_store_dwordx4 v186, v[100:103], s[100:101]
	s_add_u32 s100, s100, 0x2000
	s_addc_u32 s101, s101, 0
	global_store_dwordx4 v186, v[92:95], s[100:101]
	s_add_u32 s100, s100, 0x2000
	s_addc_u32 s101, s101, 0
	global_store_dwordx4 v186, v[96:99], s[100:101]
	s_add_u32 s100, s100, 0x2000
	s_addc_u32 s101, s101, 0
	global_store_dwordx4 v186, v[88:91], s[100:101]
	s_add_u32 s100, s100, 0x2000
	s_addc_u32 s101, s101, 0
	global_store_dwordx4 v186, v[84:87], s[100:101]
	s_add_u32 s100, s100, 0x2000
	s_addc_u32 s101, s101, 0
	global_store_dwordx4 v186, v[76:79], s[100:101]
	s_add_u32 s100, s100, 0x2000
	s_addc_u32 s101, s101, 0
	global_store_dwordx4 v186, v[80:83], s[100:101]
	s_add_u32 s100, s100, 0x2000
	s_addc_u32 s101, s101, 0
	global_store_dwordx4 v186, v[72:75], s[100:101]
	s_add_u32 s100, s100, 0x2000
	s_addc_u32 s101, s101, 0
	global_store_dwordx4 v186, v[68:71], s[100:101]
	s_add_u32 s100, s100, 0x2000
	s_addc_u32 s101, s101, 0
	global_store_dwordx4 v186, v[64:67], s[100:101]
	s_add_u32 s100, s100, 0x2000
	s_addc_u32 s101, s101, 0
	global_store_dwordx4 v186, v[60:63], s[100:101]
	s_add_u32 s100, s100, 0x2000
	s_addc_u32 s101, s101, 0
	global_store_dwordx4 v186, v[56:59], s[100:101]
	s_add_u32 s100, s100, 0x2000
	s_addc_u32 s101, s101, 0
	global_store_dwordx4 v186, v[52:55], s[100:101]
	s_add_u32 s100, s100, 0x2000
	s_addc_u32 s101, s101, 0
	global_store_dwordx4 v186, v[44:47], s[100:101]
	s_add_u32 s100, s100, 0x2000
	s_addc_u32 s101, s101, 0
	global_store_dwordx4 v186, v[48:51], s[100:101]
	s_add_u32 s100, s100, 0x2000
	s_addc_u32 s101, s101, 0
	global_store_dwordx4 v186, v[40:43], s[100:101]
	s_add_u32 s100, s100, 0x2000
	s_addc_u32 s101, s101, 0
	global_store_dwordx4 v186, v[36:39], s[100:101]
	s_add_u32 s100, s100, 0x2000
	s_addc_u32 s101, s101, 0
	global_store_dwordx4 v186, v[28:31], s[100:101]
	s_add_u32 s100, s100, 0x2000
	s_addc_u32 s101, s101, 0
	global_store_dwordx4 v186, v[32:35], s[100:101]
	s_add_u32 s100, s100, 0x2000
	s_addc_u32 s101, s101, 0
	global_store_dwordx4 v186, v[24:27], s[100:101]
	s_add_u32 s100, s100, 0x2000
	s_addc_u32 s101, s101, 0
	global_store_dwordx4 v186, v[20:23], s[100:101]
	s_add_u32 s100, s100, 0x2000
	s_addc_u32 s101, s101, 0
	global_store_dwordx4 v186, v[12:15], s[100:101]
	s_add_u32 s100, s100, 0x2000
	s_addc_u32 s101, s101, 0
	global_store_dwordx4 v186, v[16:19], s[100:101]
	s_add_u32 s100, s100, 0x2000
	s_addc_u32 s101, s101, 0
	global_store_dwordx4 v186, v[8:11], s[100:101]
	s_add_u32 s100, s100, 0x2000
	s_addc_u32 s101, s101, 0
	global_store_dwordx4 v186, v[4:7], s[100:101]
	s_add_u32 s100, s100, 0x2000
	s_addc_u32 s101, s101, 0
	global_store_dwordx4 v186, v[0:3], s[100:101]
	s_add_u32 s100, s100, 0x2000
	s_addc_u32 s101, s101, 0
	s_waitcnt vmcnt(0)
	buffer_wbl2 sc1
	s_waitcnt vmcnt(0)
	s_and_b32 s6, s2, 0x7f
	s_lshl_b32 s6, s6, 6
	s_lshl_b32 s7, s98, 14
	s_add_u32 s6, s6, s7
	s_add_u32 s6, s6, 0x29702000
	s_add_u32 s6, s46, s6
	s_addc_u32 s7, s47, 0
	v_mov_b32_e32 v187, 0
	v_mov_b32_e32 v188, 1
	s_mov_b64 exec, 1
	global_atomic_add v187, v188, s[6:7]
	s_mov_b64 exec, -1
	s_branch .Lm2_epi_tail
